# RESID phases: software prefetch of next row Y and X16 loads before the wave reductions
# speedup vs baseline: 1.0027x; 1.0027x over previous
; __device__ __forceinline__ float wave_sum(float v) {
; #pragma unroll
;     for (int o = 1; o < 64; o <<= 1) v += __shfl_xor(v, o);
;     return v;
; }
; __device__ __forceinline__ void resid_rows(const Params& p, const bf16_t* Y, const float* cs, const float* post_g, float alpha, bool first, const float* next_g, bf16_t* XN, bf16_t* X16,
;                                            int gw, int NGW, int lane) {
;     const bool last = (next_g == nullptr);
;     f32x4 pg[8], ng[8];
; #pragma unroll
;     for (int j = 0; j < 4; ++j) { pg[2 * j] = *(const f32x4*)(post_g + j * 512 + lane * 8); pg[2 * j + 1] = *(const f32x4*)(post_g + j * 512 + lane * 8 + 4); }
;     if (cs) {
; #pragma unroll
;         for (int j = 0; j < 4; ++j) { pg[2 * j] *= *(const f32x4*)(cs + j * 512 + lane * 8); pg[2 * j + 1] *= *(const f32x4*)(cs + j * 512 + lane * 8 + 4); }
;     }
;     if (next_g) {
; #pragma unroll
;         for (int j = 0; j < 4; ++j) { ng[2 * j] = *(const f32x4*)(next_g + j * 512 + lane * 8); ng[2 * j + 1] = *(const f32x4*)(next_g + j * 512 + lane * 8 + 4); }
;     }
;     for (int r = gw; r < T; r += NGW) {
;         u32x4 yw[4]; f32x4 xv[8];
; #pragma unroll
;         for (int j = 0; j < 4; ++j) yw[j] = *(const u32x4*)(Y + (size_t)r * DM + j * 512 + lane * 8);
;         if (first) { const float* xr = xin_row(p, r);
; #pragma unroll
;             for (int j = 0; j < 4; ++j) { xv[2 * j] = *(const f32x4*)(xr + j * 512 + lane * 8); xv[2 * j + 1] = *(const f32x4*)(xr + j * 512 + lane * 8 + 4); }
;         } else { u32x4 xw[4];
; #pragma unroll
;             for (int j = 0; j < 4; ++j) xw[j] = *(const u32x4*)(X16 + (size_t)r * DM + j * 512 + lane * 8);
.LBB0_180:
	s_movk_i32 s30, 0x1000
	s_cmp_gt_i32 s58, 0xbfff
	s_cbranch_scc1 .LBB0_191
	v_and_b32_e32 v67, 64, v190
	v_add_u32_e32 v67, 64, v67
	v_xor_b32_e32 v68, 1, v190
	v_cmp_lt_i32_e32 vcc, v68, v67
	s_ashr_i32 s59, s58, 31
	s_xor_b64 s[4:5], s[24:25], -1
	v_cndmask_b32_e32 v68, v190, v68, vcc
	v_lshlrev_b32_e32 v120, 2, v68
	v_xor_b32_e32 v68, 2, v190
	v_cmp_lt_i32_e32 vcc, v68, v67
	s_ashr_i32 s73, s72, 31
	s_lshl_b64 s[6:7], s[58:59], 13
	v_cndmask_b32_e32 v68, v190, v68, vcc
	v_lshlrev_b32_e32 v121, 2, v68
	v_xor_b32_e32 v68, 4, v190
	v_cmp_lt_i32_e32 vcc, v68, v67
	v_readlane_b32 s8, v248, 20
	s_add_u32 s6, s8, s6
	v_cndmask_b32_e32 v68, v190, v68, vcc
	v_lshlrev_b32_e32 v122, 2, v68
	v_xor_b32_e32 v68, 8, v190
	v_cmp_lt_i32_e32 vcc, v68, v67
	v_readlane_b32 s8, v248, 21
	s_load_dwordx4 s[24:27], s[0:1], 0x120
	v_cndmask_b32_e32 v68, v190, v68, vcc
	v_lshlrev_b32_e32 v123, 2, v68
	v_xor_b32_e32 v68, 16, v190
	v_cmp_lt_i32_e32 vcc, v68, v67
	s_addc_u32 s7, s8, s7
	s_lshl_b64 s[16:17], s[58:59], 12
	v_cndmask_b32_e32 v68, v190, v68, vcc
	v_lshlrev_b32_e32 v124, 2, v68
	v_xor_b32_e32 v68, 32, v190
	v_cmp_lt_i32_e32 vcc, v68, v67
	v_lshlrev_b32_e32 v116, 4, v191
	v_mov_b32_e32 v117, v1
	v_cndmask_b32_e32 v67, v190, v68, vcc
	v_lshlrev_b32_e32 v125, 2, v67
	v_mov_b32_e32 v67, v1
	v_lshl_add_u64 v[114:115], s[6:7], 0, v[66:67]
	s_lshl_b64 s[6:7], s[72:73], 13
	s_add_u32 s8, s28, s16
	s_addc_u32 s9, s29, s17
	s_waitcnt lgkmcnt(0)
	s_add_u32 s8, s26, s8
	s_addc_u32 s9, s27, s9
	s_lshl_b64 s[10:11], s[72:73], 12
	s_add_u32 s12, s12, s16
	s_addc_u32 s13, s13, s17
	s_mov_b64 s[16:17], s[58:59]
	s_and_b64 vcc, exec, s[4:5]
	s_cbranch_vccz .LBB0_184
	v_lshl_add_u64 v[228:229], s[12:13], 0, v[116:117]
	global_load_dwordx4 v[196:199], v[228:229], off
	global_load_dwordx4 v[200:203], v[228:229], off offset:1024
	global_load_dwordx4 v[204:207], v[228:229], off offset:2048
	global_load_dwordx4 v[208:211], v[228:229], off offset:3072
	s_add_u32 vcc_lo, s8, 0x10300000
	s_addc_u32 vcc_hi, s9, 0
	v_lshl_add_u64 v[228:229], vcc, 0, v[116:117]
	global_load_dwordx4 v[212:215], v[228:229], off
	global_load_dwordx4 v[216:219], v[228:229], off offset:1024
	global_load_dwordx4 v[220:223], v[228:229], off offset:2048
	global_load_dwordx4 v[224:227], v[228:229], off offset:3072
	s_waitcnt vmcnt(0)
	s_branch .LBB0_184

; __device__ __forceinline__ f32x4 ylo(const u32x4 w) { return (f32x4){bflo(w.x), bfhi(w.x), bflo(w.y), bfhi(w.y)}; }
; __device__ __forceinline__ f32x4 yhi(const u32x4 w) { return (f32x4){bflo(w.z), bfhi(w.z), bflo(w.w), bfhi(w.w)}; }
; __device__ __forceinline__ void resid_rows(const Params& p, const bf16_t* Y, const float* cs, const float* post_g, float alpha, bool first, const float* next_g, bf16_t* XN, bf16_t* X16,
;                                            int gw, int NGW, int lane) {
;     ...
;     for (int r = gw; r < T; r += NGW) {
;         u32x4 yw[4]; f32x4 xv[8];
; #pragma unroll
;         for (int j = 0; j < 4; ++j) yw[j] = *(const u32x4*)(Y + (size_t)r * DM + j * 512 + lane * 8);
;         if (first) { const float* xr = xin_row(p, r);
; #pragma unroll
;             for (int j = 0; j < 4; ++j) { xv[2 * j] = *(const f32x4*)(xr + j * 512 + lane * 8); xv[2 * j + 1] = *(const f32x4*)(xr + j * 512 + lane * 8 + 4); }
;         } else { u32x4 xw[4];
; #pragma unroll
;             for (int j = 0; j < 4; ++j) xw[j] = *(const u32x4*)(X16 + (size_t)r * DM + j * 512 + lane * 8);
; #pragma unroll
;             for (int j = 0; j < 4; ++j) { xv[2 * j] = ylo(xw[j]); xv[2 * j + 1] = yhi(xw[j]); }
;         }
.LBB0_184:
	s_and_b64 vcc, exec, s[4:5]
	s_cbranch_vccnz .Lresid_pf
	v_lshl_add_u64 v[66:67], s[12:13], 0, v[116:117]
	global_load_dwordx4 v[110:113], v[66:67], off
	global_load_dwordx4 v[106:109], v[66:67], off offset:1024
	global_load_dwordx4 v[102:105], v[66:67], off offset:2048
	global_load_dwordx4 v[98:101], v[66:67], off offset:3072
	s_mov_b64 s[18:19], -1
	s_and_b64 vcc, exec, s[4:5]
	v_lshl_add_u64 v[118:119], s[8:9], 0, v[116:117]
	s_cbranch_vccz .LBB0_186
	v_add_co_u32_e32 v70, vcc, 0x10300000, v118
	s_mov_b64 s[18:19], 0
	s_nop 0
	v_addc_co_u32_e32 v71, vcc, 0, v119, vcc
	global_load_dwordx4 v[66:69], v[70:71], off
	global_load_dwordx4 v[74:77], v[70:71], off offset:1024
	global_load_dwordx4 v[78:81], v[70:71], off offset:2048
	global_load_dwordx4 v[126:129], v[70:71], off offset:3072
	s_waitcnt vmcnt(3)
	v_lshlrev_b32_e32 v70, 16, v66
	v_and_b32_e32 v71, 0xffff0000, v66
	v_lshlrev_b32_e32 v72, 16, v67
	v_and_b32_e32 v73, 0xffff0000, v67
	v_lshlrev_b32_e32 v82, 16, v68
	v_and_b32_e32 v83, 0xffff0000, v68
	v_lshlrev_b32_e32 v84, 16, v69
	v_and_b32_e32 v85, 0xffff0000, v69
	s_waitcnt vmcnt(2)
	v_lshlrev_b32_e32 v94, 16, v74
	v_and_b32_e32 v95, 0xffff0000, v74
	v_lshlrev_b32_e32 v96, 16, v75
	v_and_b32_e32 v97, 0xffff0000, v75
	v_lshlrev_b32_e32 v90, 16, v76
	v_and_b32_e32 v91, 0xffff0000, v76
	v_lshlrev_b32_e32 v92, 16, v77
	v_and_b32_e32 v93, 0xffff0000, v77
	s_waitcnt vmcnt(1)
	v_lshlrev_b32_e32 v86, 16, v78
	v_and_b32_e32 v87, 0xffff0000, v78
	v_lshlrev_b32_e32 v88, 16, v79
	v_and_b32_e32 v89, 0xffff0000, v79
	v_lshlrev_b32_e32 v78, 16, v80
	v_and_b32_e32 v79, 0xffff0000, v80
	v_lshlrev_b32_e32 v80, 16, v81
	v_and_b32_e32 v81, 0xffff0000, v81
	s_waitcnt vmcnt(0)
	v_lshlrev_b32_e32 v74, 16, v126
	v_and_b32_e32 v75, 0xffff0000, v126
	v_lshlrev_b32_e32 v76, 16, v127
	v_and_b32_e32 v77, 0xffff0000, v127
	v_lshlrev_b32_e32 v66, 16, v128
	v_and_b32_e32 v67, 0xffff0000, v128
	v_lshlrev_b32_e32 v68, 16, v129
	v_and_b32_e32 v69, 0xffff0000, v129

; __device__ __forceinline__ f32x4 ylo(const u32x4 w) { return (f32x4){bflo(w.x), bfhi(w.x), bflo(w.y), bfhi(w.y)}; }
; __device__ __forceinline__ f32x4 yhi(const u32x4 w) { return (f32x4){bflo(w.z), bfhi(w.z), bflo(w.w), bfhi(w.w)}; }
; __device__ __forceinline__ float sq4(const f32x4 t) { return (t.x * t.x + t.y * t.y) + (t.z * t.z + t.w * t.w); }
; __device__ __forceinline__ float wave_sum(float v) {
; #pragma unroll
;     for (int o = 1; o < 64; o <<= 1) v += __shfl_xor(v, o);
;     return v;
; }
; __device__ __forceinline__ void resid_rows(const Params& p, const bf16_t* Y, const float* cs, const float* post_g, float alpha, bool first, const float* next_g, bf16_t* XN, bf16_t* X16,
;                                            int gw, int NGW, int lane) {
;     ...
;         float ss = 0.f;
;         if (cs) {
; #pragma unroll
;             for (int j = 0; j < 4; ++j) ss += sq4(ylo(yw[j]) * *(const f32x4*)(cs + j * 512 + lane * 8)) + sq4(yhi(yw[j]) * *(const f32x4*)(cs + j * 512 + lane * 8 + 4));
;         } else {
; #pragma unroll
;             for (int j = 0; j < 4; ++j) ss += sq4(ylo(yw[j])) + sq4(yhi(yw[j]));
;         }
;         const float rs = alpha * rsqrtf(wave_sum(ss) * (1.f / DM) + EPS); float ss2 = 0.f;
; #pragma unroll
;         for (int j = 0; j < 4; ++j) { xv[2 * j] += (ylo(yw[j]) * rs) * pg[2 * j]; xv[2 * j + 1] += (yhi(yw[j]) * rs) * pg[2 * j + 1]; ss2 += sq4(xv[2 * j]) + sq4(xv[2 * j + 1]); }
.Lresid_after_wait:
	v_lshlrev_b32_e32 v146, 16, v98
	v_and_b32_e32 v147, 0xffff0000, v98
	v_pk_mul_f32 v[136:137], v[106:107], v[106:107]
	v_pk_mul_f32 v[140:141], v[108:109], v[108:109]
	v_mul_f32_e32 v150, v146, v146
	v_mul_f32_e32 v151, v147, v147
	v_pk_add_f32 v[128:129], v[128:129], v[128:129] op_sel:[0,1] op_sel_hi:[1,0]
	v_pk_add_f32 v[132:133], v[132:133], v[132:133] op_sel:[0,1] op_sel_hi:[1,0]
	v_pk_fma_f32 v[136:137], v[134:135], v[134:135], v[136:137]
	v_pk_fma_f32 v[140:141], v[138:139], v[138:139], v[140:141]
	v_lshlrev_b32_e32 v98, 16, v99
	v_and_b32_e32 v99, 0xffff0000, v99
	v_mov_b32_e32 v129, v150
	v_mov_b32_e32 v133, v151
	v_mul_f32_e32 v152, v98, v98
	v_mul_f32_e32 v153, v99, v99
	v_pk_add_f32 v[128:129], v[128:129], v[132:133]
	v_pk_add_f32 v[132:133], v[136:137], v[136:137] op_sel:[0,1] op_sel_hi:[1,0]
	v_pk_add_f32 v[136:137], v[140:141], v[140:141] op_sel:[0,1] op_sel_hi:[1,0]
	v_mov_b32_e32 v133, v152
	v_mov_b32_e32 v137, v153
	v_lshlrev_b32_e32 v142, 16, v102
	v_and_b32_e32 v143, 0xffff0000, v102
	v_lshlrev_b32_e32 v102, 16, v103
	v_and_b32_e32 v103, 0xffff0000, v103
	v_pk_add_f32 v[132:133], v[132:133], v[136:137]
	v_lshlrev_b32_e32 v148, 16, v100
	v_and_b32_e32 v149, 0xffff0000, v100
	v_pk_add_f32 v[128:129], v[128:129], v[132:133]
	v_mul_f32_e32 v132, v143, v143
	v_mul_f32_e32 v136, v103, v103
	v_mul_f32_e32 v154, v148, v148
	v_mul_f32_e32 v155, v149, v149
	v_pk_fma_f32 v[132:133], v[142:143], v[142:143], v[132:133] op_sel_hi:[1,1,0]
	v_pk_fma_f32 v[136:137], v[102:103], v[102:103], v[136:137] op_sel_hi:[1,1,0]
	v_lshlrev_b32_e32 v144, 16, v104
	v_and_b32_e32 v145, 0xffff0000, v104
	v_lshlrev_b32_e32 v104, 16, v105
	v_and_b32_e32 v105, 0xffff0000, v105
	v_mov_b32_e32 v133, v154
	v_mov_b32_e32 v137, v155
	v_lshlrev_b32_e32 v100, 16, v101
	v_and_b32_e32 v101, 0xffff0000, v101
	v_pk_add_f32 v[132:133], v[132:133], v[136:137]
	v_mul_f32_e32 v136, v145, v145
	v_mul_f32_e32 v140, v105, v105
	v_mul_f32_e32 v156, v100, v100
	v_mul_f32_e32 v157, v101, v101
	v_pk_fma_f32 v[136:137], v[144:145], v[144:145], v[136:137] op_sel_hi:[1,1,0]
	v_pk_fma_f32 v[140:141], v[104:105], v[104:105], v[140:141] op_sel_hi:[1,1,0]
	v_mov_b32_e32 v137, v156
	v_mov_b32_e32 v141, v157
	v_pk_add_f32 v[136:137], v[136:137], v[140:141]
	s_nop 0
	v_pk_add_f32 v[132:133], v[132:133], v[136:137]
	s_nop 0
	v_pk_add_f32 v[128:129], v[128:129], v[132:133]
	v_mov_b32_e32 v133, v110
	v_add_f32_e32 v128, v128, v129
	ds_bpermute_b32 v129, v120, v128
	v_mov_b32_e32 v110, v127
	v_mov_b32_e32 v132, v126
	s_waitcnt lgkmcnt(0)
	v_add_f32_e32 v128, v128, v129
	ds_bpermute_b32 v129, v121, v128
	s_waitcnt lgkmcnt(0)
	v_add_f32_e32 v128, v128, v129
	ds_bpermute_b32 v129, v122, v128
	s_waitcnt lgkmcnt(0)
	v_add_f32_e32 v128, v128, v129
	ds_bpermute_b32 v129, v123, v128
	s_waitcnt lgkmcnt(0)
	v_add_f32_e32 v128, v128, v129
	ds_bpermute_b32 v129, v124, v128
	s_waitcnt lgkmcnt(0)
	v_add_f32_e32 v128, v128, v129
	ds_bpermute_b32 v129, v125, v128
	s_waitcnt lgkmcnt(0)
	v_add_f32_e32 v128, v128, v129
	v_fmamk_f32 v128, v128, 0x3a000000, v185
	v_mul_f32_e32 v129, 0x4b800000, v128
	v_cmp_gt_f32_e32 vcc, s57, v128
	s_nop 1
	v_cndmask_b32_e32 v128, v128, v129, vcc
	v_rsq_f32_e32 v128, v128
	s_nop 0
	v_mul_f32_e32 v129, 0x45800000, v128
	v_cndmask_b32_e32 v128, v128, v129, vcc
	v_mul_f32_e32 v128, s31, v128
	v_pk_mul_f32 v[110:111], v[128:129], v[110:111] op_sel_hi:[0,1]
	v_pk_fma_f32 v[72:73], v[8:9], v[110:111], v[72:73]
	v_mov_b32_e32 v110, v130
	v_mov_b32_e32 v111, v112
	v_pk_mul_f32 v[110:111], v[128:129], v[110:111] op_sel_hi:[0,1]
	v_pk_fma_f32 v[82:83], v[2:3], v[110:111], v[82:83]
	v_mov_b32_e32 v111, v106
	v_mov_b32_e32 v106, v135
	v_pk_mul_f32 v[106:107], v[128:129], v[106:107] op_sel_hi:[0,1]
	v_pk_fma_f32 v[96:97], v[16:17], v[106:107], v[96:97]
	v_mov_b32_e32 v106, v138
	v_mov_b32_e32 v107, v108
	v_pk_mul_f32 v[102:103], v[128:129], v[102:103] op_sel_hi:[0,1]
	v_mov_b32_e32 v112, v131
	v_mov_b32_e32 v110, v134
	v_pk_mul_f32 v[106:107], v[128:129], v[106:107] op_sel_hi:[0,1]
	v_mov_b32_e32 v108, v139
	v_pk_fma_f32 v[88:89], v[20:21], v[102:103], v[88:89]
	v_pk_mul_f32 v[102:103], v[128:129], v[144:145] op_sel_hi:[0,1]
	v_pk_mul_f32 v[98:99], v[128:129], v[98:99] op_sel_hi:[0,1]
	v_pk_mul_f32 v[132:133], v[128:129], v[132:133] op_sel_hi:[0,1]
	v_pk_mul_f32 v[112:113], v[128:129], v[112:113] op_sel_hi:[0,1]
	v_pk_mul_f32 v[110:111], v[128:129], v[110:111] op_sel_hi:[0,1]
	v_pk_mul_f32 v[108:109], v[128:129], v[108:109] op_sel_hi:[0,1]
	v_pk_fma_f32 v[90:91], v[10:11], v[106:107], v[90:91]
	v_pk_mul_f32 v[106:107], v[128:129], v[142:143] op_sel_hi:[0,1]
	v_pk_mul_f32 v[104:105], v[128:129], v[104:105] op_sel_hi:[0,1]
	v_pk_fma_f32 v[78:79], v[22:23], v[102:103], v[78:79]
	v_pk_mul_f32 v[102:103], v[128:129], v[146:147] op_sel_hi:[0,1]
	v_pk_fma_f32 v[76:77], v[28:29], v[98:99], v[76:77]
	v_pk_mul_f32 v[98:99], v[128:129], v[148:149] op_sel_hi:[0,1]
	v_pk_mul_f32 v[100:101], v[128:129], v[100:101] op_sel_hi:[0,1]
	v_pk_fma_f32 v[70:71], v[6:7], v[132:133], v[70:71]
	v_pk_fma_f32 v[84:85], v[4:5], v[112:113], v[84:85]
	v_pk_fma_f32 v[94:95], v[14:15], v[110:111], v[94:95]
	v_pk_fma_f32 v[92:93], v[12:13], v[108:109], v[92:93]
	v_pk_fma_f32 v[86:87], v[18:19], v[106:107], v[86:87]
	v_pk_fma_f32 v[80:81], v[24:25], v[104:105], v[80:81]
	v_pk_fma_f32 v[74:75], v[26:27], v[102:103], v[74:75]
	v_pk_fma_f32 v[68:69], v[32:33], v[100:101], v[68:69]
	s_andn2_b64 vcc, exec, s[2:3]
	v_pk_fma_f32 v[66:67], v[30:31], v[98:99], v[66:67]
	s_cbranch_vccnz .LBB0_190
; __device__ __forceinline__ unsigned cvt_pk_bf16(float lo, float hi) { unsigned r; asm volatile("v_cvt_pk_bf16_f32 %0, %1, %2" : "=v"(r) : "v"(lo), "v"(hi)); return r; }
; __device__ __forceinline__ void resid_rows(const Params& p, const bf16_t* Y, const float* cs, const float* post_g, float alpha, bool first, const float* next_g, bf16_t* XN, bf16_t* X16,
;                                            int gw, int NGW, int lane) {
;     ...
;         if (last) { float* xo = p.out + (size_t)r * DM;
; #pragma unroll
;             for (int j = 0; j < 4; ++j) { *(f32x4*)(xo + j * 512 + lane * 8) = xv[2 * j]; *(f32x4*)(xo + j * 512 + lane * 8 + 4) = xv[2 * j + 1]; }
;         } else {
; #pragma unroll
;             for (int j = 0; j < 4; ++j) { const f32x4 a = xv[2 * j], b = xv[2 * j + 1];
;                 u32x4 w; w.x = cvt_pk_bf16(a.x, a.y); w.y = cvt_pk_bf16(a.z, a.w); w.z = cvt_pk_bf16(b.x, b.y); w.w = cvt_pk_bf16(b.z, b.w);
;                 *(u32x4*)(X16 + (size_t)r * DM + j * 512 + lane * 8) = w; }
;             const float r2 = rsqrtf(wave_sum(ss2) * (1.f / DM) + EPS);
; #pragma unroll
;             for (int j = 0; j < 4; ++j) { const f32x4 a = (xv[2 * j] * r2) * ng[2 * j], b = (xv[2 * j + 1] * r2) * ng[2 * j + 1];
;                 u32x4 w; w.x = cvt_pk_bf16(a.x, a.y); w.y = cvt_pk_bf16(a.z, a.w); w.z = cvt_pk_bf16(b.x, b.y); w.w = cvt_pk_bf16(b.z, b.w);
;                 *(u32x4*)(XN + (size_t)r * DM + j * 512 + lane * 8) = w; }
;         }
;     }
	v_pk_mul_f32 v[98:99], v[84:85], v[84:85]
	v_pk_mul_f32 v[100:101], v[82:83], v[82:83]
	s_mov_b32 s15, 0x10300000
	v_pk_mov_b32 v[102:103], v[100:101], v[98:99] op_sel:[1,0]
	v_mov_b32_e32 v101, v99
	v_pk_add_f32 v[98:99], v[102:103], v[100:101]
	v_pk_mul_f32 v[100:101], v[72:73], v[72:73]
	v_pk_mul_f32 v[102:103], v[70:71], v[70:71]
	v_pk_add_f32 v[98:99], v[98:99], v[98:99] op_sel_hi:[0,1]
	v_pk_mov_b32 v[104:105], v[102:103], v[100:101] op_sel:[1,0]
	v_mov_b32_e32 v103, v101
	v_pk_add_f32 v[100:101], v[104:105], v[102:103]
	v_pk_mul_f32 v[102:103], v[92:93], v[92:93]
	v_pk_mul_f32 v[104:105], v[90:91], v[90:91]
	v_mul_f32_e32 v98, v78, v78
	v_pk_mov_b32 v[106:107], v[104:105], v[102:103] op_sel:[1,0]
	v_mov_b32_e32 v105, v103
	v_pk_add_f32 v[102:103], v[106:107], v[104:105]
	v_pk_mul_f32 v[104:105], v[96:97], v[96:97]
	v_pk_mul_f32 v[106:107], v[94:95], v[94:95]
	v_pk_add_f32 v[100:101], v[100:101], v[100:101] op_sel_hi:[0,1]
	v_pk_mov_b32 v[108:109], v[106:107], v[104:105] op_sel:[1,0]
	v_mov_b32_e32 v107, v105
	v_pk_add_f32 v[104:105], v[108:109], v[106:107]
	v_pk_fma_f32 v[106:107], v[78:79], v[78:79], v[98:99] op_sel_hi:[1,1,0]
	v_mul_f32_e32 v98, v80, v80
	v_pk_fma_f32 v[108:109], v[80:81], v[80:81], v[98:99] op_sel_hi:[1,1,0]
	v_mul_f32_e32 v98, v86, v86
	v_pk_fma_f32 v[110:111], v[86:87], v[86:87], v[98:99] op_sel_hi:[1,1,0]
	v_mul_f32_e32 v98, v88, v88
	v_pk_add_f32 v[102:103], v[102:103], v[102:103] op_sel_hi:[0,1]
	v_pk_add_f32 v[104:105], v[104:105], v[104:105] op_sel_hi:[0,1]
	v_pk_fma_f32 v[112:113], v[88:89], v[88:89], v[98:99] op_sel_hi:[1,1,0]
	v_mul_f32_e32 v106, v66, v66
	v_mul_f32_e32 v108, v67, v67
	v_mul_f32_e32 v110, v68, v68
	v_mul_f32_e32 v112, v69, v69
	v_mul_f32_e32 v98, v74, v74
	v_mul_f32_e32 v100, v75, v75
	v_mul_f32_e32 v102, v76, v76
	v_mul_f32_e32 v104, v77, v77
	v_pk_add_f32 v[106:107], v[106:107], v[108:109]
	v_pk_add_f32 v[108:109], v[110:111], v[112:113]
	v_pk_add_f32 v[98:99], v[98:99], v[100:101]
	v_pk_add_f32 v[100:101], v[102:103], v[104:105]
	v_pk_add_f32 v[106:107], v[106:107], v[108:109]
	v_pk_add_f32 v[98:99], v[98:99], v[100:101]
	s_nop 0
	v_pk_add_f32 v[98:99], v[106:107], v[98:99]
	s_nop 0
	v_add_f32_e32 v98, v98, v99
	ds_bpermute_b32 v99, v120, v98
	s_waitcnt lgkmcnt(0)
	v_add_f32_e32 v102, v98, v99
	ds_bpermute_b32 v103, v121, v102
	v_cvt_pk_bf16_f32 v98, v70, v71
	v_cvt_pk_bf16_f32 v99, v72, v73
	v_cvt_pk_bf16_f32 v100, v82, v83
	v_cvt_pk_bf16_f32 v101, v84, v85
	s_waitcnt lgkmcnt(0)
	v_add_f32_e32 v104, v102, v103
	ds_bpermute_b32 v105, v122, v104
	v_add_co_u32_e32 v102, vcc, s15, v118
	s_mov_b32 s15, 0x4300000
	s_nop 0
	v_addc_co_u32_e32 v103, vcc, 0, v119, vcc
	s_waitcnt lgkmcnt(0)
	v_add_f32_e32 v104, v104, v105
	ds_bpermute_b32 v105, v123, v104
	global_store_dwordx4 v[102:103], v[98:101], off
	s_waitcnt lgkmcnt(0)
	v_add_f32_e32 v104, v104, v105
	ds_bpermute_b32 v105, v124, v104
	v_cvt_pk_bf16_f32 v98, v94, v95
	v_cvt_pk_bf16_f32 v99, v96, v97
	v_cvt_pk_bf16_f32 v100, v90, v91
	v_cvt_pk_bf16_f32 v101, v92, v93
	s_waitcnt lgkmcnt(0)
	v_add_f32_e32 v104, v104, v105
	ds_bpermute_b32 v105, v125, v104
	global_store_dwordx4 v[102:103], v[98:101], off offset:1024
	s_nop 1
	v_cvt_pk_bf16_f32 v98, v86, v87
	v_cvt_pk_bf16_f32 v99, v88, v89
	v_cvt_pk_bf16_f32 v100, v78, v79
	v_cvt_pk_bf16_f32 v101, v80, v81
	global_store_dwordx4 v[102:103], v[98:101], off offset:2048
	s_waitcnt lgkmcnt(0)
	s_nop 0
	v_add_f32_e32 v100, v104, v105
	v_fmamk_f32 v100, v100, 0x3a000000, v185
	v_mul_f32_e32 v101, 0x4b800000, v100
	v_cmp_gt_f32_e32 vcc, s57, v100
	v_cvt_pk_bf16_f32 v98, v74, v75
	v_cvt_pk_bf16_f32 v99, v76, v77
	s_nop 1
	v_cndmask_b32_e32 v100, v100, v101, vcc
	v_rsq_f32_e32 v104, v100
	v_cvt_pk_bf16_f32 v100, v66, v67
	v_cvt_pk_bf16_f32 v101, v68, v69
	global_store_dwordx4 v[102:103], v[98:101], off offset:3072
	s_nop 1
	v_mul_f32_e32 v98, 0x45800000, v104
	v_cndmask_b32_e32 v102, v104, v98, vcc
	v_pk_mul_f32 v[98:99], v[70:71], v[102:103] op_sel_hi:[1,0]
	v_pk_mul_f32 v[100:101], v[72:73], v[102:103] op_sel_hi:[1,0]
	v_pk_mul_f32 v[104:105], v[82:83], v[102:103] op_sel_hi:[1,0]
	v_pk_mul_f32 v[100:101], v[36:37], v[100:101]
	v_pk_mul_f32 v[98:99], v[34:35], v[98:99]
	v_pk_mul_f32 v[104:105], v[38:39], v[104:105]
	v_pk_mul_f32 v[106:107], v[84:85], v[102:103] op_sel_hi:[1,0]
	v_cvt_pk_bf16_f32 v98, v98, v99
	v_cvt_pk_bf16_f32 v99, v100, v101
	v_cvt_pk_bf16_f32 v100, v104, v105
	v_add_co_u32_e32 v104, vcc, s15, v118
	v_pk_mul_f32 v[106:107], v[40:41], v[106:107]
	s_nop 0
	v_addc_co_u32_e32 v105, vcc, 0, v119, vcc
	v_cvt_pk_bf16_f32 v101, v106, v107
	global_store_dwordx4 v[104:105], v[98:101], off
	v_pk_mul_f32 v[106:107], v[90:91], v[102:103] op_sel_hi:[1,0]
	v_pk_mul_f32 v[108:109], v[92:93], v[102:103] op_sel_hi:[1,0]
	v_pk_mul_f32 v[98:99], v[94:95], v[102:103] op_sel_hi:[1,0]
	v_pk_mul_f32 v[100:101], v[96:97], v[102:103] op_sel_hi:[1,0]
	v_pk_mul_f32 v[98:99], v[42:43], v[98:99]
	v_pk_mul_f32 v[100:101], v[44:45], v[100:101]
	v_pk_mul_f32 v[108:109], v[48:49], v[108:109]
	v_pk_mul_f32 v[106:107], v[46:47], v[106:107]
	v_cvt_pk_bf16_f32 v98, v98, v99
	v_cvt_pk_bf16_f32 v99, v100, v101
	s_nop 0
	v_cvt_pk_bf16_f32 v100, v106, v107
	v_cvt_pk_bf16_f32 v101, v108, v109
	global_store_dwordx4 v[104:105], v[98:101], off offset:1024
	v_pk_mul_f32 v[106:107], v[78:79], v[102:103] op_sel_hi:[1,0]
	v_pk_mul_f32 v[108:109], v[80:81], v[102:103] op_sel_hi:[1,0]
	v_pk_mul_f32 v[98:99], v[86:87], v[102:103] op_sel_hi:[1,0]
	v_pk_mul_f32 v[100:101], v[88:89], v[102:103] op_sel_hi:[1,0]
	v_pk_mul_f32 v[98:99], v[50:51], v[98:99]
	v_pk_mul_f32 v[100:101], v[52:53], v[100:101]
	v_pk_mul_f32 v[108:109], v[56:57], v[108:109]
	v_pk_mul_f32 v[106:107], v[54:55], v[106:107]
	v_cvt_pk_bf16_f32 v98, v98, v99
	v_cvt_pk_bf16_f32 v99, v100, v101
	s_nop 0
	v_cvt_pk_bf16_f32 v100, v106, v107
	v_cvt_pk_bf16_f32 v101, v108, v109
	global_store_dwordx4 v[104:105], v[98:101], off offset:2048
	v_pk_mul_f32 v[106:107], v[66:67], v[102:103] op_sel_hi:[1,0]
	s_nop 0
	v_pk_mul_f32 v[98:99], v[74:75], v[102:103] op_sel_hi:[1,0]
	v_pk_mul_f32 v[100:101], v[76:77], v[102:103] op_sel_hi:[1,0]
	v_pk_mul_f32 v[98:99], v[58:59], v[98:99]
	v_pk_mul_f32 v[100:101], v[60:61], v[100:101]
	v_pk_mul_f32 v[102:103], v[68:69], v[102:103] op_sel_hi:[1,0]
	v_pk_mul_f32 v[106:107], v[62:63], v[106:107]
	v_pk_mul_f32 v[102:103], v[64:65], v[102:103]
	v_cvt_pk_bf16_f32 v98, v98, v99
	v_cvt_pk_bf16_f32 v99, v100, v101
	v_cvt_pk_bf16_f32 v100, v106, v107
	s_nop 0
	v_cvt_pk_bf16_f32 v101, v102, v103
	global_store_dwordx4 v[104:105], v[98:101], off offset:3072
	s_cbranch_execnz .LBB0_183
	s_branch .LBB0_182

; __device__ __forceinline__ f32x4 ylo(const u32x4 w) { return (f32x4){bflo(w.x), bfhi(w.x), bflo(w.y), bfhi(w.y)}; }
; __device__ __forceinline__ f32x4 yhi(const u32x4 w) { return (f32x4){bflo(w.z), bfhi(w.z), bflo(w.w), bfhi(w.w)}; }
; __device__ __forceinline__ void resid_rows(const Params& p, const bf16_t* Y, const float* cs, const float* post_g, float alpha, bool first, const float* next_g, bf16_t* XN, bf16_t* X16,
;                                            int gw, int NGW, int lane) {
;     ...
;     for (int r = gw; r < T; r += NGW) {
;         u32x4 yw[4]; f32x4 xv[8];
; #pragma unroll
;         for (int j = 0; j < 4; ++j) yw[j] = *(const u32x4*)(Y + (size_t)r * DM + j * 512 + lane * 8);
;         if (first) { const float* xr = xin_row(p, r);
; #pragma unroll
;             for (int j = 0; j < 4; ++j) { xv[2 * j] = *(const f32x4*)(xr + j * 512 + lane * 8); xv[2 * j + 1] = *(const f32x4*)(xr + j * 512 + lane * 8 + 4); }
;         } else { u32x4 xw[4];
; #pragma unroll
;             for (int j = 0; j < 4; ++j) xw[j] = *(const u32x4*)(X16 + (size_t)r * DM + j * 512 + lane * 8);
; #pragma unroll
;             for (int j = 0; j < 4; ++j) { xv[2 * j] = ylo(xw[j]); xv[2 * j + 1] = yhi(xw[j]); }
;         }
.Lresid_pf:
	v_lshl_add_u64 v[118:119], s[8:9], 0, v[116:117]
	s_waitcnt vmcnt(8)
	v_mov_b64_e32 v[110:111], v[196:197]
	v_mov_b64_e32 v[112:113], v[198:199]
	v_mov_b64_e32 v[106:107], v[200:201]
	v_mov_b64_e32 v[108:109], v[202:203]
	v_mov_b64_e32 v[102:103], v[204:205]
	v_mov_b64_e32 v[104:105], v[206:207]
	v_mov_b64_e32 v[98:99], v[208:209]
	v_mov_b64_e32 v[100:101], v[210:211]
	v_mov_b64_e32 v[66:67], v[212:213]
	v_mov_b64_e32 v[68:69], v[214:215]
	v_mov_b64_e32 v[74:75], v[216:217]
	v_mov_b64_e32 v[76:77], v[218:219]
	v_mov_b64_e32 v[78:79], v[220:221]
	v_mov_b64_e32 v[80:81], v[222:223]
	v_mov_b64_e32 v[126:127], v[224:225]
	v_mov_b64_e32 v[128:129], v[226:227]
	s_add_u32 s15, s16, s72
	s_cmp_gt_i32 s15, 0xbfff
	s_cbranch_scc1 .Lresid_pf_skip
	s_add_u32 vcc_lo, s12, s10
	s_addc_u32 vcc_hi, s13, s11
	v_lshl_add_u64 v[228:229], vcc, 0, v[116:117]
	global_load_dwordx4 v[196:199], v[228:229], off
	global_load_dwordx4 v[200:203], v[228:229], off offset:1024
	global_load_dwordx4 v[204:207], v[228:229], off offset:2048
	global_load_dwordx4 v[208:211], v[228:229], off offset:3072
	s_add_u32 vcc_lo, s8, s10
	s_addc_u32 vcc_hi, s9, s11
	s_add_u32 vcc_lo, vcc_lo, 0x10300000
	s_addc_u32 vcc_hi, vcc_hi, 0
	v_lshl_add_u64 v[228:229], vcc, 0, v[116:117]
	global_load_dwordx4 v[212:215], v[228:229], off
	global_load_dwordx4 v[216:219], v[228:229], off offset:1024
	global_load_dwordx4 v[220:223], v[228:229], off offset:2048
	global_load_dwordx4 v[224:227], v[228:229], off offset:3072
.Lresid_pf_skip:
	v_lshlrev_b32_e32 v70, 16, v66
	v_and_b32_e32 v71, 0xffff0000, v66
	v_lshlrev_b32_e32 v72, 16, v67
	v_and_b32_e32 v73, 0xffff0000, v67
	v_lshlrev_b32_e32 v82, 16, v68
	v_and_b32_e32 v83, 0xffff0000, v68
	v_lshlrev_b32_e32 v84, 16, v69
	v_and_b32_e32 v85, 0xffff0000, v69
	v_lshlrev_b32_e32 v94, 16, v74
	v_and_b32_e32 v95, 0xffff0000, v74
	v_lshlrev_b32_e32 v96, 16, v75
	v_and_b32_e32 v97, 0xffff0000, v75
	v_lshlrev_b32_e32 v90, 16, v76
	v_and_b32_e32 v91, 0xffff0000, v76
	v_lshlrev_b32_e32 v92, 16, v77
	v_and_b32_e32 v93, 0xffff0000, v77
	v_lshlrev_b32_e32 v86, 16, v78
	v_and_b32_e32 v87, 0xffff0000, v78
	v_lshlrev_b32_e32 v88, 16, v79
	v_and_b32_e32 v89, 0xffff0000, v79
	v_lshlrev_b32_e32 v78, 16, v80
	v_and_b32_e32 v79, 0xffff0000, v80
	v_lshlrev_b32_e32 v80, 16, v81
	v_and_b32_e32 v81, 0xffff0000, v81
	v_lshlrev_b32_e32 v74, 16, v126
	v_and_b32_e32 v75, 0xffff0000, v126
	v_lshlrev_b32_e32 v76, 16, v127
	v_and_b32_e32 v77, 0xffff0000, v127
	v_lshlrev_b32_e32 v66, 16, v128
	v_and_b32_e32 v67, 0xffff0000, v128
	v_lshlrev_b32_e32 v68, 16, v129
	v_and_b32_e32 v69, 0xffff0000, v129
	v_lshlrev_b32_e32 v127, 16, v111
	v_lshlrev_b32_e32 v126, 16, v110
	v_and_b32_e32 v111, 0xffff0000, v111
	v_and_b32_e32 v110, 0xffff0000, v110
	v_lshlrev_b32_e32 v131, 16, v113
	v_lshlrev_b32_e32 v130, 16, v112
	v_and_b32_e32 v113, 0xffff0000, v113
	v_and_b32_e32 v112, 0xffff0000, v112
	v_pk_mul_f32 v[128:129], v[110:111], v[110:111]
	v_pk_mul_f32 v[132:133], v[112:113], v[112:113]
	v_pk_fma_f32 v[128:129], v[126:127], v[126:127], v[128:129]
	v_pk_fma_f32 v[132:133], v[130:131], v[130:131], v[132:133]
	v_lshlrev_b32_e32 v135, 16, v107
	v_lshlrev_b32_e32 v134, 16, v106
	v_and_b32_e32 v107, 0xffff0000, v107
	v_and_b32_e32 v106, 0xffff0000, v106
	v_lshlrev_b32_e32 v139, 16, v109
	v_lshlrev_b32_e32 v138, 16, v108
	v_and_b32_e32 v109, 0xffff0000, v109
	v_and_b32_e32 v108, 0xffff0000, v108
	s_branch .Lresid_after_wait
